# first K-fragment LDS read of each attention step hoisted above the DMA issue block (on top of V-read hoist version)
# speedup vs baseline: 1.0047x; 1.0003x over previous
; __device__ __forceinline__ int v_rd_base(int lane) { return ((lane & 3) << 3) | (((lane >> 2) & 3) << 6) | (((lane >> 4) & 1) << 5) | (((lane >> 5) & 1) << 8); }
; #define DMA_K(t, slot) do { glds16(ksrc[0] + (long)(t) * 65536, (unsigned)__builtin_amdgcn_readfirstlane(kdst + (slot) * SHM_K)); \
;     glds16(ksrc[1] + (long)(t) * 65536, (unsigned)__builtin_amdgcn_readfirstlane(kdst + (slot) * SHM_K + 1024)); \
;     glds16(krsrc + (long)(t) * 4096, (unsigned)__builtin_amdgcn_readfirstlane(krdst + (slot) * SHM_KR)); } while (0)
; __device__ __forceinline__ void qkt(f32x16& p0, f32x16& p1, const char* Ks, const char* Krs, const bf16x8* qr, const char* qro, int r32, int hi, const f32x16& negm) {
;     p0 = negm; p1 = negm;
; #pragma unroll
;     for (int d0 = 0; d0 < 8; ++d0) { const int cb = (d0 * 16 + hi * 8) * 2;
;         const bf16x8 b0 = *reinterpret_cast<const bf16x8*>(Ks + KSWZ(r32, cb));
;         const bf16x8 b1 = *reinterpret_cast<const bf16x8*>(Ks + KSWZ(32 + r32, cb));
;         p0 = __builtin_amdgcn_mfma_f32_32x32x16_bf16(b0, qr[d0], p0, 0, 0, 0);
;         p1 = __builtin_amdgcn_mfma_f32_32x32x16_bf16(b1, qr[d0], p1, 0, 0, 0); }
; #pragma unroll
;     for (int d0 = 0; d0 < 4; ++d0) { const int cb = (d0 * 16 + hi * 8) * 2;
;         const bf16x8 b0 = *reinterpret_cast<const bf16x8*>(Krs + KRSWZ(r32, cb));
;         const bf16x8 b1 = *reinterpret_cast<const bf16x8*>(Krs + KRSWZ(32 + r32, cb));
;         const bf16x8 qf = qr[8 + d0];
;         p0 = __builtin_amdgcn_mfma_f32_32x32x16_bf16(b0, qf, p0, 0, 0, 0);
;         p1 = __builtin_amdgcn_mfma_f32_32x32x16_bf16(b1, qf, p1, 0, 0, 0); }
; }
; __device__ __forceinline__ void attn_unit(const bf16_t* __restrict__ Qb, const bf16_t* __restrict__ Kh, const bf16_t* __restrict__ Vh, const bf16_t* __restrict__ Krh, ...
;     ...
;     const int vb0 = (int)(uintptr_t)V_lds + v_rd_base(lane);
;     const int NT = seq / 64;
;     ...
;     f32x16 p0, p1; float al = 1.f, mn_; bf16x8 pa0, pa1, pa2, pa3;
;     asm volatile("s_waitcnt vmcnt(0) lgkmcnt(0)" ::: "memory");
;     DMA_K(0, 0); DMA_V(0, 0); DMA_K(1, 1);
;     WAIT_BAR(0);
;     int s0 = 2, s1 = 0, s2 = 1;
;     for (int j = 0; j < NT; ++j) {
;         if (j + 1 < NT) DMA_V(j + 1, s2);
;         if (j + 2 < NT) DMA_K(j + 2, s0);
;         qkt(p0, p1, K_lds + s1 * SHM_K, Kr_lds + s1 * SHM_KR, qr, qro, r32, hi, negm);
.LBB0_396:
	s_mov_b32 s6, s70
	s_lshl_b32 s7, s6, 14
	s_add_i32 s10, s7, 0
	v_add3_u32 v68, s10, v227, v211
	ds_read_b128 v[64:67], v68
	s_lshl_b32 s74, vcc_lo, 14
	v_add_u32_e32 v245, s74, v228
	s_lshl_b32 s72, s71, 14
	v_readfirstlane_b32 s100, v245
	s_mov_b32 s101, m0
	s_mov_b32 m0, s100
	s_nop 0
	global_load_lds_dwordx4 v[208:209], off
	s_mov_b32 m0, s101
	s_addk_i32 s100, 0x400
	v_add_u32_e32 v245, s72, v213
	s_mov_b32 s101, m0
	s_mov_b32 m0, s100
	s_nop 0
	global_load_lds_dwordx4 v[206:207], off
	s_mov_b32 m0, s101
	s_lshl_b32 s73, s71, 13
	v_readfirstlane_b32 s100, v245
	s_mov_b32 s101, m0
	s_mov_b32 m0, s100
	s_nop 0
	global_load_lds_dwordx4 v[204:205], off
	s_mov_b32 m0, s101
	s_addk_i32 s100, 0x400
	v_add_u32_e32 v245, s73, v212
	s_mov_b32 s101, m0
	s_mov_b32 m0, s100
	s_nop 0
	global_load_lds_dwordx4 v[202:203], off
	s_mov_b32 m0, s101
	v_readfirstlane_b32 s100, v245
	s_mov_b32 s101, m0
	s_mov_b32 m0, s100
	s_nop 0
	global_load_lds_dwordx4 v[200:201], off
	s_mov_b32 m0, s101
	s_waitcnt lgkmcnt(0)
	v_mfma_f32_32x32x16_bf16 v[112:127], v[64:67], v[128:131], v[80:95]
	ds_read_b128 v[64:67], v68 offset:8192
	v_add3_u32 v68, s10, v226, v211
	s_lshl_b32 s11, s6, 13
	s_mov_b32 s70, vcc_lo
	s_waitcnt lgkmcnt(0)
	v_mfma_f32_32x32x16_bf16 v[96:111], v[64:67], v[128:131], v[80:95]
	ds_read_b128 v[64:67], v68
	s_waitcnt lgkmcnt(0)
	v_mfma_f32_32x32x16_bf16 v[112:127], v[64:67], v[132:135], v[112:127]
	ds_read_b128 v[64:67], v68 offset:8192
	v_add3_u32 v68, s10, v225, v211
	s_waitcnt lgkmcnt(0)
	v_mfma_f32_32x32x16_bf16 v[96:111], v[64:67], v[132:135], v[96:111]
	ds_read_b128 v[64:67], v68
	s_waitcnt lgkmcnt(0)
	v_mfma_f32_32x32x16_bf16 v[112:127], v[64:67], v[136:139], v[112:127]
	ds_read_b128 v[64:67], v68 offset:8192
	v_add3_u32 v68, s10, v224, v211
	s_waitcnt lgkmcnt(0)
	v_mfma_f32_32x32x16_bf16 v[96:111], v[64:67], v[136:139], v[96:111]
	ds_read_b128 v[64:67], v68
	s_waitcnt lgkmcnt(0)
	v_mfma_f32_32x32x16_bf16 v[112:127], v[64:67], v[140:143], v[112:127]
	ds_read_b128 v[64:67], v68 offset:8192
	v_add3_u32 v68, s10, v223, v211
	s_waitcnt lgkmcnt(0)
	v_mfma_f32_32x32x16_bf16 v[96:111], v[64:67], v[140:143], v[96:111]
	ds_read_b128 v[64:67], v68
	s_waitcnt lgkmcnt(0)
	v_mfma_f32_32x32x16_bf16 v[112:127], v[64:67], v[144:147], v[112:127]
	ds_read_b128 v[64:67], v68 offset:8192
	v_add3_u32 v68, s10, v222, v211
	s_waitcnt lgkmcnt(0)
	v_mfma_f32_32x32x16_bf16 v[96:111], v[64:67], v[144:147], v[96:111]
	ds_read_b128 v[64:67], v68
	s_waitcnt lgkmcnt(0)
	v_mfma_f32_32x32x16_bf16 v[112:127], v[64:67], v[148:151], v[112:127]
	ds_read_b128 v[64:67], v68 offset:8192
	v_add3_u32 v68, s10, v221, v211
	s_waitcnt lgkmcnt(0)
	v_mfma_f32_32x32x16_bf16 v[96:111], v[64:67], v[148:151], v[96:111]
	ds_read_b128 v[64:67], v68
	s_waitcnt lgkmcnt(0)
	v_mfma_f32_32x32x16_bf16 v[112:127], v[64:67], v[152:155], v[112:127]
	ds_read_b128 v[64:67], v68 offset:8192
	v_add3_u32 v68, s10, v220, v211
	s_sub_i32 s10, s10, s11
	s_waitcnt lgkmcnt(0)
	v_mfma_f32_32x32x16_bf16 v[96:111], v[64:67], v[152:155], v[96:111]
	ds_read_b128 v[64:67], v68
	s_waitcnt lgkmcnt(0)
	v_mfma_f32_32x32x16_bf16 v[112:127], v[64:67], v[156:159], v[112:127]
	ds_read_b128 v[64:67], v68 offset:8192
	v_add3_u32 v68, s10, v219, v215
	s_waitcnt lgkmcnt(0)
	v_mfma_f32_32x32x16_bf16 v[96:111], v[64:67], v[156:159], v[96:111]
	ds_read_b128 v[64:67], v68 offset:49152
	s_waitcnt lgkmcnt(0)
	v_mfma_f32_32x32x16_bf16 v[112:127], v[64:67], v[164:167], v[112:127]
	ds_read_b128 v[64:67], v68 offset:53248
	v_add3_u32 v68, s10, v218, v215
	s_waitcnt lgkmcnt(0)
	v_mfma_f32_32x32x16_bf16 v[96:111], v[64:67], v[164:167], v[96:111]
	ds_read_b128 v[64:67], v68 offset:49152
	s_waitcnt lgkmcnt(0)
	v_mfma_f32_32x32x16_bf16 v[112:127], v[64:67], v[172:175], v[112:127]
	ds_read_b128 v[64:67], v68 offset:53248
	v_add3_u32 v68, s10, v217, v215
	s_waitcnt lgkmcnt(0)
	v_mfma_f32_32x32x16_bf16 v[96:111], v[64:67], v[172:175], v[96:111]
	ds_read_b128 v[64:67], v68 offset:49152
	s_waitcnt lgkmcnt(0)
	v_mfma_f32_32x32x16_bf16 v[112:127], v[64:67], v[160:163], v[112:127]
	ds_read_b128 v[64:67], v68 offset:53248
	v_add3_u32 v68, s10, v216, v215
	s_waitcnt lgkmcnt(0)
	v_mfma_f32_32x32x16_bf16 v[96:111], v[64:67], v[160:163], v[96:111]
	ds_read_b128 v[64:67], v68 offset:49152
	s_waitcnt lgkmcnt(0)
	v_mfma_f32_32x32x16_bf16 v[112:127], v[64:67], v[168:171], v[112:127]
	ds_read_b128 v[64:67], v68 offset:53248
	s_waitcnt lgkmcnt(0)
	v_mfma_f32_32x32x16_bf16 v[96:111], v[64:67], v[168:171], v[96:111]
	s_nop 8
	v_max_f32_e32 v68, v113, v113
	v_max_f32_e32 v69, v112, v112
	v_max_f32_e32 v68, v69, v68
	v_max_f32_e32 v69, v121, v121
	v_max_f32_e32 v70, v120, v120
	v_max_f32_e32 v69, v70, v69
	v_max3_f32 v66, v68, v114, v115
	v_max_f32_e32 v64, v105, v105
	v_max_f32_e32 v65, v104, v104
	v_max_f32_e32 v64, v65, v64
	v_max3_f32 v65, v96, v97, v98
	v_max3_f32 v64, v64, v106, v107
	v_max3_f32 v67, v69, v122, v123
	v_max3_f32 v65, v65, v99, v100
	v_max3_f32 v64, v64, v108, v109
	v_max3_f32 v66, v66, v116, v117
	v_max3_f32 v67, v67, v124, v125
	v_max3_f32 v65, v65, v101, v102
	v_max3_f32 v64, v64, v110, v111
	v_max3_f32 v66, v66, v118, v119
	v_max3_f32 v67, v67, v126, v127
	v_max3_f32 v64, v65, v103, v64
	v_max3_f32 v64, v66, v67, v64
	v_mov_b32_e32 v65, v64
	s_nop 1
	v_permlane32_swap_b32_e32 v64, v65
	v_max_f32_e32 v65, v65, v65
	v_max_f32_e32 v64, v64, v64
	v_max_f32_e32 v64, v64, v65
	v_cmp_ge_f32_e32 vcc, s92, v64
	s_cmp_eq_u64 vcc, exec
	s_cbranch_scc0 .LBB0_404
	v_mov_b32_e32 v229, 1.0

; __global__ void __launch_bounds__(512, 2) fwd_kernel(Args args) {
;     extern __shared__ __attribute__((aligned(16))) unsigned char lds[];
	.amdhsa_kernel _Z10fwd_kernel4Args
		.amdhsa_group_segment_fixed_size 0
		.amdhsa_private_segment_fixed_size 0
		.amdhsa_kernarg_size 440
		.amdhsa_user_sgpr_count 2
		.amdhsa_user_sgpr_dispatch_ptr 0
		.amdhsa_user_sgpr_queue_ptr 0
		.amdhsa_user_sgpr_kernarg_segment_ptr 1
		.amdhsa_user_sgpr_dispatch_id 0
		.amdhsa_user_sgpr_kernarg_preload_length 0
		.amdhsa_user_sgpr_kernarg_preload_offset 0
		.amdhsa_user_sgpr_private_segment_size 0
		.amdhsa_uses_dynamic_stack 0
		.amdhsa_enable_private_segment 0
		.amdhsa_system_sgpr_workgroup_id_x 1
		.amdhsa_system_sgpr_workgroup_id_y 0
		.amdhsa_system_sgpr_workgroup_id_z 0
		.amdhsa_system_sgpr_workgroup_info 0
		.amdhsa_system_vgpr_workitem_id 2
		.amdhsa_next_free_vgpr 246
		.amdhsa_next_free_sgpr 102
		.amdhsa_accum_offset 248
		.amdhsa_reserve_vcc 1
		.amdhsa_float_round_mode_32 0
		.amdhsa_float_round_mode_16_64 0
		.amdhsa_float_denorm_mode_32 3
		.amdhsa_float_denorm_mode_16_64 3
		.amdhsa_dx10_clamp 1
		.amdhsa_ieee_mode 1
		.amdhsa_fp16_overflow 0
		.amdhsa_tg_split 0
		.amdhsa_exception_fp_ieee_invalid_op 0
		.amdhsa_exception_fp_denorm_src 0
		.amdhsa_exception_fp_ieee_div_zero 0
		.amdhsa_exception_fp_ieee_overflow 0
		.amdhsa_exception_fp_ieee_underflow 0
		.amdhsa_exception_fp_ieee_inexact 0
		.amdhsa_exception_int_div_zero 0
	.end_amdhsa_kernel

; __global__ void __launch_bounds__(512, 2) fwd_kernel(Args args) {
;     extern __shared__ __attribute__((aligned(16))) unsigned char lds[];
amdhsa.kernels:
  - .agpr_count:     0
    .args:
      - .offset:         0
        .size:           184
        .value_kind:     by_value
      - .offset:         184
        .size:           4
        .value_kind:     hidden_block_count_x
      - .offset:         188
        .size:           4
        .value_kind:     hidden_block_count_y
      - .offset:         192
        .size:           4
        .value_kind:     hidden_block_count_z
      - .offset:         196
        .size:           2
        .value_kind:     hidden_group_size_x
      - .offset:         198
        .size:           2
        .value_kind:     hidden_group_size_y
      - .offset:         200
        .size:           2
        .value_kind:     hidden_group_size_z
      - .offset:         202
        .size:           2
        .value_kind:     hidden_remainder_x
      - .offset:         204
        .size:           2
        .value_kind:     hidden_remainder_y
      - .offset:         206
        .size:           2
        .value_kind:     hidden_remainder_z
      - .offset:         224
        .size:           8
        .value_kind:     hidden_global_offset_x
      - .offset:         232
        .size:           8
        .value_kind:     hidden_global_offset_y
      - .offset:         240
        .size:           8
        .value_kind:     hidden_global_offset_z
      - .offset:         248
        .size:           2
        .value_kind:     hidden_grid_dims
      - .offset:         272
        .size:           8
        .value_kind:     hidden_multigrid_sync_arg
      - .offset:         304
        .size:           4
        .value_kind:     hidden_dynamic_lds_size
    .group_segment_fixed_size: 0
    .kernarg_segment_align: 8
    .kernarg_segment_size: 440
    .language:       OpenCL C
    .language_version:
      - 2
      - 0
    .max_flat_workgroup_size: 512
    .name:           _Z10fwd_kernel4Args
    .private_segment_fixed_size: 0
    .sgpr_count:     108
    .sgpr_spill_count: 35
    .symbol:         _Z10fwd_kernel4Args.kd
    .uniform_work_group_size: 1
    .uses_dynamic_stack: false
    .vgpr_count:     246
    .vgpr_spill_count: 0
    .wavefront_size: 64
